# out/down epilogue row-sum exchanges through v_permlane swaps on top of the previous version
# baseline (speedup 1.0000x reference)
; #define LAS __attribute__((address_space(3)))
; __device__ __forceinline__ float shx(float v, int mask, int lane) { return __int_as_float(__builtin_amdgcn_ds_bpermute((lane ^ mask) << 2, __float_as_int(v))); }
; __device__ __forceinline__ u32x4 pack8(const f32x4& a, const f32x4& b) { u32x4 w; w.x = pack2(a[0], a[1]); w.y = pack2(a[2], a[3]); w.z = pack2(b[0], b[1]); w.w = pack2(b[2], b[3]); return w; }
;     __device__ __forceinline__ void operator()(AccT& acc, const pg8::Unit& u, int wr, int wc, int fr, int fq, const LAS float* rs) const {
;         int row0 = u.pm * 256 + wr * 64 + fr; asm volatile("" : "+v"(row0)); const int cb = u.pn * 256 + wc * 32 + 8 * fq, lane = fr + 16 * fq;
; #pragma unroll
;         for (int ai = 0; ai < 2; ++ai) {
;             f32x4 hv[4][2][2];
; #pragma unroll
;             for (int m = 0; m < 4; ++m)
; #pragma unroll
;                 for (int bj = 0; bj < 2; ++bj) { const float* hp = h + (size_t)(row0 + ai * 128 + m * 16) * D + cb + bj * 128; hv[m][bj][0] = *(const f32x4*)hp; hv[m][bj][1] = *(const f32x4*)(hp + 4); }
; #pragma unroll
;             for (int m = 0; m < 4; ++m) {
;                 const int row = row0 + ai * 128 + m * 16; float ss = 0.f;
; #pragma unroll
;                 for (int bj = 0; bj < 2; ++bj) {
;                     const int col = cb + bj * 128; float* hp = h + (size_t)row * D + col;
;                     const f32x4 o0 = hv[m][bj][0] + acc[ai][bj][m][0], o1 = hv[m][bj][1] + acc[ai][bj][m][1];
;                     *(f32x4*)hp = o0; *(f32x4*)(hp + 4) = o1;
;                     *(u32x4*)(hb + (size_t)row * D + col) = pack8(o0, o1);
;                     ss += o0[0] * o0[0] + o0[1] * o0[1] + o0[2] * o0[2] + o0[3] * o0[3] + o1[0] * o1[0] + o1[1] * o1[1] + o1[2] * o1[2] + o1[3] * o1[3];
;                 }
;                 ss += shx(ss, 16, lane); ss += shx(ss, 32, lane);
;                 if (fq == 0) atomicAdd(rsqn + row, ss);
;             }
;         }
;     }
.Lot_epi:
	v_lshl_or_b32 v202, s23, 8, v233
	v_lshl_add_u32 v206, s22, 8, v197
	v_ashrrev_i32_e32 v203, 31, v202
	v_lshlrev_b64 v[244:245], 2, v[202:203]
	v_ashrrev_i32_e32 v207, 31, v206
	v_lshl_add_u64 v[204:205], s[10:11], 0, v[244:245]
	v_lshlrev_b64 v[246:247], 13, v[206:207]
	v_lshl_add_u64 v[132:133], v[204:205], 0, v[246:247]
	global_load_dwordx4 v[236:239], v[132:133], off offset:16
	global_load_dwordx4 v[240:243], v[132:133], off
	global_load_dwordx4 v[180:183], v[132:133], off offset:528
	global_load_dwordx4 v[184:187], v[132:133], off offset:512
	v_add_u32_e32 v214, 16, v206
	v_ashrrev_i32_e32 v215, 31, v214
	v_add_u32_e32 v210, 32, v206
	v_add_u32_e32 v208, 48, v206
	v_lshlrev_b64 v[218:219], 13, v[214:215]
	v_ashrrev_i32_e32 v211, 31, v210
	v_ashrrev_i32_e32 v209, 31, v208
	v_lshl_add_u64 v[132:133], v[204:205], 0, v[218:219]
	v_lshlrev_b64 v[216:217], 13, v[210:211]
	v_lshlrev_b64 v[212:213], 13, v[208:209]
	global_load_dwordx4 v[172:175], v[132:133], off offset:16
	global_load_dwordx4 v[176:179], v[132:133], off
	global_load_dwordx4 v[164:167], v[132:133], off offset:528
	global_load_dwordx4 v[168:171], v[132:133], off offset:512
	v_lshl_add_u64 v[132:133], v[204:205], 0, v[216:217]
	v_lshl_add_u64 v[136:137], v[204:205], 0, v[212:213]
	global_load_dwordx4 v[156:159], v[132:133], off offset:16
	global_load_dwordx4 v[160:163], v[132:133], off
	global_load_dwordx4 v[140:143], v[132:133], off offset:528
	global_load_dwordx4 v[148:151], v[132:133], off offset:512
	global_load_dwordx4 v[144:147], v[136:137], off offset:16
	global_load_dwordx4 v[152:155], v[136:137], off
	s_nop 0
	global_load_dwordx4 v[132:135], v[136:137], off offset:528
	s_nop 0
	global_load_dwordx4 v[136:139], v[136:137], off offset:512
	v_lshl_add_u64 v[246:247], s[10:11], 0, v[246:247]
	v_lshl_add_u64 v[244:245], v[246:247], 0, v[244:245]
	s_waitcnt vmcnt(0)
	v_pk_add_f32 v[126:127], v[126:127], v[238:239]
	v_pk_add_f32 v[130:131], v[130:131], v[242:243]
	v_pk_add_f32 v[128:129], v[128:129], v[240:241]
	v_pk_add_f32 v[124:125], v[124:125], v[236:237]
	global_store_dwordx4 v[244:245], v[128:131], off
	global_store_dwordx4 v[244:245], v[124:127], off offset:16
	v_cvt_pk_bf16_f32 v236, v128, v129
	v_lshlrev_b64 v[240:241], 12, v[206:207]
	v_mul_f32_e32 v129, v129, v129
	v_fmac_f32_e32 v129, v128, v128
	v_lshl_add_u64 v[240:241], s[8:9], 0, v[240:241]
	v_fmac_f32_e32 v129, v130, v130
	v_lshl_add_u64 v[240:241], v[202:203], 1, v[240:241]
	v_fmac_f32_e32 v129, v131, v131
	v_pk_add_f32 v[122:123], v[122:123], v[186:187]
	v_pk_add_f32 v[120:121], v[120:121], v[184:185]
	v_cvt_pk_bf16_f32 v237, v130, v131
	v_cvt_pk_bf16_f32 v238, v124, v125
	v_cvt_pk_bf16_f32 v239, v126, v127
	global_store_dwordx4 v[240:241], v[236:239], off
	v_fmac_f32_e32 v129, v124, v124
	v_pk_add_f32 v[118:119], v[118:119], v[182:183]
	v_pk_add_f32 v[116:117], v[116:117], v[180:181]
	global_store_dwordx4 v[244:245], v[120:123], off offset:512
	global_store_dwordx4 v[244:245], v[116:119], off offset:528
	v_cvt_pk_bf16_f32 v124, v120, v121
	v_fmac_f32_e32 v129, v125, v125
	v_mul_f32_e32 v121, v121, v121
	v_fmac_f32_e32 v121, v120, v120
	v_fmac_f32_e32 v121, v122, v122
	v_fmac_f32_e32 v121, v123, v123
	v_fmac_f32_e32 v121, v116, v116
	v_fmac_f32_e32 v121, v117, v117
	v_fmac_f32_e32 v129, v126, v126
	v_fmac_f32_e32 v121, v118, v118
	v_fmac_f32_e32 v129, v127, v127
	v_fmac_f32_e32 v121, v119, v119
	v_cvt_pk_bf16_f32 v126, v116, v117
	v_add_f32_e32 v116, v129, v121
	v_mov_b32_e32 v117, v116
	s_nop 1
	v_permlane16_swap_b32_e32 v116, v117
	v_cvt_pk_bf16_f32 v125, v122, v123
	v_cvt_pk_bf16_f32 v127, v118, v119
	global_store_dwordx4 v[240:241], v[124:127], off offset:256
	s_waitcnt lgkmcnt(0)
	v_add_f32_e32 v116, v116, v117
	v_mov_b32_e32 v117, v116
	s_nop 1
	v_permlane32_swap_b32_e32 v116, v117
	s_and_saveexec_b64 s[22:23], s[4:5]
	s_cbranch_execz .LBB0_625
	s_waitcnt lgkmcnt(0)
	v_add_f32_e32 v118, v116, v117
	v_lshl_add_u64 v[116:117], v[206:207], 2, s[12:13]
	global_atomic_add_f32 v[116:117], v118, off
.LBB0_625:
	s_or_b64 exec, exec, s[22:23]
	s_waitcnt lgkmcnt(0)
	v_lshl_add_u64 v[116:117], s[10:11], 0, v[218:219]
	v_lshl_add_u64 v[120:121], v[202:203], 2, v[116:117]
	v_pk_add_f32 v[114:115], v[114:115], v[178:179]
	v_pk_add_f32 v[112:113], v[112:113], v[176:177]
	v_pk_add_f32 v[110:111], v[110:111], v[174:175]
	v_pk_add_f32 v[108:109], v[108:109], v[172:173]
	global_store_dwordx4 v[120:121], v[112:115], off
	global_store_dwordx4 v[120:121], v[108:111], off offset:16
	v_cvt_pk_bf16_f32 v116, v112, v113
	v_pk_add_f32 v[104:105], v[104:105], v[168:169]
	v_mul_f32_e32 v113, v113, v113
	v_fmac_f32_e32 v113, v112, v112
	v_fmac_f32_e32 v113, v114, v114
	v_fmac_f32_e32 v113, v115, v115
	v_fmac_f32_e32 v113, v108, v108
	v_cvt_pk_bf16_f32 v118, v108, v109
	v_fmac_f32_e32 v113, v109, v109
	v_pk_add_f32 v[108:109], v[100:101], v[164:165]
	v_mul_f32_e32 v100, v105, v105
	v_pk_add_f32 v[106:107], v[106:107], v[170:171]
	v_fmac_f32_e32 v100, v104, v104
	v_fmac_f32_e32 v100, v106, v106
	v_fmac_f32_e32 v100, v107, v107
	v_fmac_f32_e32 v113, v110, v110
	v_fmac_f32_e32 v100, v108, v108
	v_cvt_pk_bf16_f32 v119, v110, v111
	v_fmac_f32_e32 v113, v111, v111
	v_pk_add_f32 v[110:111], v[102:103], v[166:167]
	v_fmac_f32_e32 v100, v109, v109
	v_fmac_f32_e32 v100, v110, v110
	v_fmac_f32_e32 v100, v111, v111
	v_add_f32_e32 v100, v113, v100
	v_mov_b32_e32 v101, v100
	s_nop 1
	v_permlane16_swap_b32_e32 v100, v101
	v_lshlrev_b64 v[122:123], 12, v[214:215]
	v_lshl_add_u64 v[122:123], s[8:9], 0, v[122:123]
	v_cvt_pk_bf16_f32 v117, v114, v115
	v_lshl_add_u64 v[122:123], v[202:203], 1, v[122:123]
	s_waitcnt lgkmcnt(0)
	v_add_f32_e32 v100, v100, v101
	v_mov_b32_e32 v101, v100
	s_nop 1
	v_permlane32_swap_b32_e32 v100, v101
	global_store_dwordx4 v[122:123], v[116:119], off
	global_store_dwordx4 v[120:121], v[104:107], off offset:512
	global_store_dwordx4 v[120:121], v[108:111], off offset:528
	v_cvt_pk_bf16_f32 v102, v104, v105
	v_cvt_pk_bf16_f32 v103, v106, v107
	s_nop 0
	v_cvt_pk_bf16_f32 v104, v108, v109
	v_cvt_pk_bf16_f32 v105, v110, v111
	global_store_dwordx4 v[122:123], v[102:105], off offset:256
	s_and_saveexec_b64 s[22:23], s[4:5]
	s_cbranch_execz .LBB0_627
	s_waitcnt lgkmcnt(0)
	v_add_f32_e32 v102, v100, v101
	v_lshl_add_u64 v[100:101], v[214:215], 2, s[12:13]
	global_atomic_add_f32 v[100:101], v102, off
; __device__ __forceinline__ float shx(float v, int mask, int lane) { return __int_as_float(__builtin_amdgcn_ds_bpermute((lane ^ mask) << 2, __float_as_int(v))); }
; __device__ __forceinline__ u32x4 pack8(const f32x4& a, const f32x4& b) { u32x4 w; w.x = pack2(a[0], a[1]); w.y = pack2(a[2], a[3]); w.z = pack2(b[0], b[1]); w.w = pack2(b[2], b[3]); return w; }
;     __device__ __forceinline__ void operator()(AccT& acc, const pg8::Unit& u, int wr, int wc, int fr, int fq, const LAS float* rs) const {
;     ...
;         for (int ai = 0; ai < 2; ++ai) {
;             f32x4 hv[4][2][2];
; #pragma unroll
;             for (int m = 0; m < 4; ++m)
; #pragma unroll
;                 for (int bj = 0; bj < 2; ++bj) { const float* hp = h + (size_t)(row0 + ai * 128 + m * 16) * D + cb + bj * 128; hv[m][bj][0] = *(const f32x4*)hp; hv[m][bj][1] = *(const f32x4*)(hp + 4); }
; #pragma unroll
;             for (int m = 0; m < 4; ++m) {
;                 const int row = row0 + ai * 128 + m * 16; float ss = 0.f;
; #pragma unroll
;                 for (int bj = 0; bj < 2; ++bj) {
;                     const int col = cb + bj * 128; float* hp = h + (size_t)row * D + col;
;                     const f32x4 o0 = hv[m][bj][0] + acc[ai][bj][m][0], o1 = hv[m][bj][1] + acc[ai][bj][m][1];
;                     *(f32x4*)hp = o0; *(f32x4*)(hp + 4) = o1;
;                     *(u32x4*)(hb + (size_t)row * D + col) = pack8(o0, o1);
;                     ss += o0[0] * o0[0] + o0[1] * o0[1] + o0[2] * o0[2] + o0[3] * o0[3] + o1[0] * o1[0] + o1[1] * o1[1] + o1[2] * o1[2] + o1[3] * o1[3];
;                 }
;                 ss += shx(ss, 16, lane); ss += shx(ss, 32, lane);
;                 if (fq == 0) atomicAdd(rsqn + row, ss);
;             }
.LBB0_627:
	s_or_b64 exec, exec, s[22:23]
	s_waitcnt lgkmcnt(0)
	v_lshl_add_u64 v[100:101], s[10:11], 0, v[216:217]
	v_lshl_add_u64 v[104:105], v[202:203], 2, v[100:101]
	v_pk_add_f32 v[98:99], v[98:99], v[162:163]
	v_pk_add_f32 v[96:97], v[96:97], v[160:161]
	v_pk_add_f32 v[94:95], v[94:95], v[158:159]
	v_pk_add_f32 v[92:93], v[92:93], v[156:157]
	global_store_dwordx4 v[104:105], v[96:99], off
	global_store_dwordx4 v[104:105], v[92:95], off offset:16
	v_cvt_pk_bf16_f32 v100, v96, v97
	v_pk_add_f32 v[88:89], v[88:89], v[148:149]
	v_mul_f32_e32 v97, v97, v97
	v_fmac_f32_e32 v97, v96, v96
	v_fmac_f32_e32 v97, v98, v98
	v_fmac_f32_e32 v97, v99, v99
	v_fmac_f32_e32 v97, v92, v92
	v_cvt_pk_bf16_f32 v102, v92, v93
	v_fmac_f32_e32 v97, v93, v93
	v_pk_add_f32 v[92:93], v[84:85], v[140:141]
	v_mul_f32_e32 v84, v89, v89
	v_pk_add_f32 v[90:91], v[90:91], v[150:151]
	v_fmac_f32_e32 v84, v88, v88
	v_fmac_f32_e32 v84, v90, v90
	v_fmac_f32_e32 v84, v91, v91
	v_fmac_f32_e32 v97, v94, v94
	v_fmac_f32_e32 v84, v92, v92
	v_cvt_pk_bf16_f32 v103, v94, v95
	v_fmac_f32_e32 v97, v95, v95
	v_pk_add_f32 v[94:95], v[86:87], v[142:143]
	v_fmac_f32_e32 v84, v93, v93
	v_fmac_f32_e32 v84, v94, v94
	v_fmac_f32_e32 v84, v95, v95
	v_add_f32_e32 v84, v97, v84
	v_mov_b32_e32 v85, v84
	s_nop 1
	v_permlane16_swap_b32_e32 v84, v85
	v_lshlrev_b64 v[106:107], 12, v[210:211]
	v_lshl_add_u64 v[106:107], s[8:9], 0, v[106:107]
	v_cvt_pk_bf16_f32 v101, v98, v99
	v_lshl_add_u64 v[106:107], v[202:203], 1, v[106:107]
	s_waitcnt lgkmcnt(0)
	v_add_f32_e32 v84, v84, v85
	v_mov_b32_e32 v85, v84
	s_nop 1
	v_permlane32_swap_b32_e32 v84, v85
	global_store_dwordx4 v[106:107], v[100:103], off
	global_store_dwordx4 v[104:105], v[88:91], off offset:512
	global_store_dwordx4 v[104:105], v[92:95], off offset:528
	v_cvt_pk_bf16_f32 v86, v88, v89
	v_cvt_pk_bf16_f32 v87, v90, v91
	s_nop 0
	v_cvt_pk_bf16_f32 v88, v92, v93
	v_cvt_pk_bf16_f32 v89, v94, v95
	global_store_dwordx4 v[106:107], v[86:89], off offset:256
	s_and_saveexec_b64 s[22:23], s[4:5]
	s_cbranch_execz .LBB0_629
	s_waitcnt lgkmcnt(0)
	v_add_f32_e32 v86, v84, v85
	v_lshl_add_u64 v[84:85], v[210:211], 2, s[12:13]
	global_atomic_add_f32 v[84:85], v86, off
.LBB0_629:
	s_or_b64 exec, exec, s[22:23]
	s_waitcnt lgkmcnt(0)
	v_lshl_add_u64 v[84:85], s[10:11], 0, v[212:213]
	v_lshl_add_u64 v[88:89], v[202:203], 2, v[84:85]
	v_pk_add_f32 v[82:83], v[82:83], v[154:155]
	v_pk_add_f32 v[80:81], v[80:81], v[152:153]
	v_pk_add_f32 v[78:79], v[78:79], v[146:147]
	v_pk_add_f32 v[76:77], v[76:77], v[144:145]
	global_store_dwordx4 v[88:89], v[80:83], off
	global_store_dwordx4 v[88:89], v[76:79], off offset:16
	v_cvt_pk_bf16_f32 v84, v80, v81
	v_pk_add_f32 v[72:73], v[72:73], v[136:137]
	v_mul_f32_e32 v81, v81, v81
	v_fmac_f32_e32 v81, v80, v80
	v_fmac_f32_e32 v81, v82, v82
	v_fmac_f32_e32 v81, v83, v83
	v_fmac_f32_e32 v81, v76, v76
	v_cvt_pk_bf16_f32 v86, v76, v77
	v_fmac_f32_e32 v81, v77, v77
	v_pk_add_f32 v[76:77], v[68:69], v[132:133]
	v_mul_f32_e32 v68, v73, v73
	v_pk_add_f32 v[74:75], v[74:75], v[138:139]
	v_fmac_f32_e32 v68, v72, v72
	v_fmac_f32_e32 v68, v74, v74
	v_fmac_f32_e32 v68, v75, v75
	v_fmac_f32_e32 v81, v78, v78
	v_fmac_f32_e32 v68, v76, v76
	v_cvt_pk_bf16_f32 v87, v78, v79
	v_fmac_f32_e32 v81, v79, v79
	v_pk_add_f32 v[78:79], v[70:71], v[134:135]
	v_fmac_f32_e32 v68, v77, v77
	v_fmac_f32_e32 v68, v78, v78
	v_fmac_f32_e32 v68, v79, v79
	v_add_f32_e32 v68, v81, v68
	v_mov_b32_e32 v69, v68
	s_nop 1
	v_permlane16_swap_b32_e32 v68, v69
	v_lshlrev_b64 v[90:91], 12, v[208:209]
	v_lshl_add_u64 v[90:91], s[8:9], 0, v[90:91]
	v_cvt_pk_bf16_f32 v85, v82, v83
	v_lshl_add_u64 v[90:91], v[202:203], 1, v[90:91]
	s_waitcnt lgkmcnt(0)
	v_add_f32_e32 v68, v68, v69
	v_mov_b32_e32 v69, v68
	s_nop 1
	v_permlane32_swap_b32_e32 v68, v69
	global_store_dwordx4 v[90:91], v[84:87], off
	global_store_dwordx4 v[88:89], v[72:75], off offset:512
	global_store_dwordx4 v[88:89], v[76:79], off offset:528
	v_cvt_pk_bf16_f32 v70, v72, v73
	v_cvt_pk_bf16_f32 v71, v74, v75
	s_nop 0
	v_cvt_pk_bf16_f32 v72, v76, v77
	v_cvt_pk_bf16_f32 v73, v78, v79
	global_store_dwordx4 v[90:91], v[70:73], off offset:256
	s_and_saveexec_b64 s[22:23], s[4:5]
	s_cbranch_execz .LBB0_631
	s_waitcnt lgkmcnt(0)
	v_add_f32_e32 v70, v68, v69
	v_lshl_add_u64 v[68:69], v[208:209], 2, s[12:13]
	global_atomic_add_f32 v[68:69], v70, off
; __device__ __forceinline__ float shx(float v, int mask, int lane) { return __int_as_float(__builtin_amdgcn_ds_bpermute((lane ^ mask) << 2, __float_as_int(v))); }
; __device__ __forceinline__ u32x4 pack8(const f32x4& a, const f32x4& b) { u32x4 w; w.x = pack2(a[0], a[1]); w.y = pack2(a[2], a[3]); w.z = pack2(b[0], b[1]); w.w = pack2(b[2], b[3]); return w; }
;     __device__ __forceinline__ void operator()(AccT& acc, const pg8::Unit& u, int wr, int wc, int fr, int fq, const LAS float* rs) const {
;     ...
;         for (int ai = 0; ai < 2; ++ai) {
;             f32x4 hv[4][2][2];
; #pragma unroll
;             for (int m = 0; m < 4; ++m)
; #pragma unroll
;                 for (int bj = 0; bj < 2; ++bj) { const float* hp = h + (size_t)(row0 + ai * 128 + m * 16) * D + cb + bj * 128; hv[m][bj][0] = *(const f32x4*)hp; hv[m][bj][1] = *(const f32x4*)(hp + 4); }
; #pragma unroll
;             for (int m = 0; m < 4; ++m) {
;                 const int row = row0 + ai * 128 + m * 16; float ss = 0.f;
; #pragma unroll
;                 for (int bj = 0; bj < 2; ++bj) {
;                     const int col = cb + bj * 128; float* hp = h + (size_t)row * D + col;
;                     const f32x4 o0 = hv[m][bj][0] + acc[ai][bj][m][0], o1 = hv[m][bj][1] + acc[ai][bj][m][1];
;                     *(f32x4*)hp = o0; *(f32x4*)(hp + 4) = o1;
;                     *(u32x4*)(hb + (size_t)row * D + col) = pack8(o0, o1);
;                     ss += o0[0] * o0[0] + o0[1] * o0[1] + o0[2] * o0[2] + o0[3] * o0[3] + o1[0] * o1[0] + o1[1] * o1[1] + o1[2] * o1[2] + o1[3] * o1[3];
;                 }
;                 ss += shx(ss, 16, lane); ss += shx(ss, 32, lane);
;                 if (fq == 0) atomicAdd(rsqn + row, ss);
;             }
.LBB0_631:
	s_or_b64 exec, exec, s[22:23]
	v_add_u32_e32 v134, 0x80, v206
	v_ashrrev_i32_e32 v135, 31, v134
	v_lshlrev_b64 v[146:147], 13, v[134:135]
	s_waitcnt lgkmcnt(0)
	v_lshl_add_u64 v[68:69], v[204:205], 0, v[146:147]
	global_load_dwordx4 v[138:141], v[68:69], off offset:16
	global_load_dwordx4 v[142:145], v[68:69], off
	global_load_dwordx4 v[116:119], v[68:69], off offset:528
	global_load_dwordx4 v[120:123], v[68:69], off offset:512
	v_add_u32_e32 v130, 0x90, v206
	v_ashrrev_i32_e32 v131, 31, v130
	v_add_u32_e32 v126, 0xa0, v206
	v_add_u32_e32 v124, 0xb0, v206
	v_lshlrev_b64 v[136:137], 13, v[130:131]
	v_ashrrev_i32_e32 v127, 31, v126
	v_ashrrev_i32_e32 v125, 31, v124
	v_lshl_add_u64 v[68:69], v[204:205], 0, v[136:137]
	v_lshlrev_b64 v[132:133], 13, v[126:127]
	v_lshlrev_b64 v[128:129], 13, v[124:125]
	global_load_dwordx4 v[108:111], v[68:69], off offset:16
	global_load_dwordx4 v[112:115], v[68:69], off
	global_load_dwordx4 v[100:103], v[68:69], off offset:528
	global_load_dwordx4 v[104:107], v[68:69], off offset:512
	v_lshl_add_u64 v[68:69], v[204:205], 0, v[132:133]
	v_lshl_add_u64 v[72:73], v[204:205], 0, v[128:129]
	global_load_dwordx4 v[92:95], v[68:69], off offset:16
	global_load_dwordx4 v[96:99], v[68:69], off
	global_load_dwordx4 v[76:79], v[68:69], off offset:528
	global_load_dwordx4 v[84:87], v[68:69], off offset:512
	global_load_dwordx4 v[80:83], v[72:73], off offset:16
	global_load_dwordx4 v[88:91], v[72:73], off
	s_nop 0
	global_load_dwordx4 v[68:71], v[72:73], off offset:528
	s_nop 0
	global_load_dwordx4 v[72:75], v[72:73], off offset:512
	v_lshl_add_u64 v[146:147], s[10:11], 0, v[146:147]
	v_lshl_add_u64 v[146:147], v[202:203], 2, v[146:147]
	s_waitcnt vmcnt(15)
	v_pk_add_f32 v[62:63], v[62:63], v[140:141]
	s_waitcnt vmcnt(14)
	v_pk_add_f32 v[66:67], v[66:67], v[144:145]
	v_pk_add_f32 v[64:65], v[64:65], v[142:143]
	v_pk_add_f32 v[60:61], v[60:61], v[138:139]
	global_store_dwordx4 v[146:147], v[64:67], off
	global_store_dwordx4 v[146:147], v[60:63], off offset:16
	v_cvt_pk_bf16_f32 v138, v64, v65
	v_lshlrev_b64 v[142:143], 12, v[134:135]
	v_mul_f32_e32 v65, v65, v65
	v_fmac_f32_e32 v65, v64, v64
	v_lshl_add_u64 v[142:143], s[8:9], 0, v[142:143]
	v_fmac_f32_e32 v65, v66, v66
	v_lshl_add_u64 v[142:143], v[202:203], 1, v[142:143]
	v_fmac_f32_e32 v65, v67, v67
	s_waitcnt vmcnt(14)
	v_pk_add_f32 v[58:59], v[58:59], v[122:123]
	v_pk_add_f32 v[56:57], v[56:57], v[120:121]
	v_cvt_pk_bf16_f32 v139, v66, v67
	v_cvt_pk_bf16_f32 v140, v60, v61
	v_cvt_pk_bf16_f32 v141, v62, v63
	global_store_dwordx4 v[142:143], v[138:141], off
	v_fmac_f32_e32 v65, v60, v60
	v_pk_add_f32 v[54:55], v[54:55], v[118:119]
	v_pk_add_f32 v[52:53], v[52:53], v[116:117]
	global_store_dwordx4 v[146:147], v[56:59], off offset:512
	global_store_dwordx4 v[146:147], v[52:55], off offset:528
	v_cvt_pk_bf16_f32 v60, v56, v57
	v_fmac_f32_e32 v65, v61, v61
	v_mul_f32_e32 v57, v57, v57
	v_fmac_f32_e32 v57, v56, v56
	v_fmac_f32_e32 v57, v58, v58
	v_fmac_f32_e32 v57, v59, v59
	v_fmac_f32_e32 v57, v52, v52
	v_fmac_f32_e32 v57, v53, v53
	v_fmac_f32_e32 v65, v62, v62
	v_fmac_f32_e32 v57, v54, v54
	v_fmac_f32_e32 v65, v63, v63
	v_fmac_f32_e32 v57, v55, v55
	v_cvt_pk_bf16_f32 v62, v52, v53
	v_add_f32_e32 v52, v65, v57
	v_mov_b32_e32 v53, v52
	s_nop 1
	v_permlane16_swap_b32_e32 v52, v53
	v_cvt_pk_bf16_f32 v61, v58, v59
	v_cvt_pk_bf16_f32 v63, v54, v55
	global_store_dwordx4 v[142:143], v[60:63], off offset:256
	s_waitcnt lgkmcnt(0)
	v_add_f32_e32 v52, v52, v53
	v_mov_b32_e32 v53, v52
	s_nop 1
	v_permlane32_swap_b32_e32 v52, v53
	s_and_saveexec_b64 s[22:23], s[4:5]
	s_cbranch_execz .LBB0_633
	s_waitcnt lgkmcnt(0)
	v_add_f32_e32 v54, v52, v53
	v_lshl_add_u64 v[52:53], v[134:135], 2, s[12:13]
	global_atomic_add_f32 v[52:53], v54, off
.LBB0_633:
	s_or_b64 exec, exec, s[22:23]
	s_waitcnt lgkmcnt(0)
	v_lshl_add_u64 v[52:53], s[10:11], 0, v[136:137]
	v_lshl_add_u64 v[56:57], v[202:203], 2, v[52:53]
	s_waitcnt vmcnt(16)
	v_pk_add_f32 v[50:51], v[50:51], v[114:115]
	v_pk_add_f32 v[48:49], v[48:49], v[112:113]
	v_pk_add_f32 v[46:47], v[46:47], v[110:111]
	v_pk_add_f32 v[44:45], v[44:45], v[108:109]
	global_store_dwordx4 v[56:57], v[48:51], off
	global_store_dwordx4 v[56:57], v[44:47], off offset:16
	v_cvt_pk_bf16_f32 v52, v48, v49
	s_waitcnt vmcnt(16)
	v_pk_add_f32 v[40:41], v[40:41], v[104:105]
	v_mul_f32_e32 v49, v49, v49
	v_fmac_f32_e32 v49, v48, v48
	v_fmac_f32_e32 v49, v50, v50
	v_fmac_f32_e32 v49, v51, v51
	v_fmac_f32_e32 v49, v44, v44
	v_cvt_pk_bf16_f32 v54, v44, v45
	v_fmac_f32_e32 v49, v45, v45
	v_pk_add_f32 v[44:45], v[36:37], v[100:101]
	v_mul_f32_e32 v36, v41, v41
	v_pk_add_f32 v[42:43], v[42:43], v[106:107]
	v_fmac_f32_e32 v36, v40, v40
	v_fmac_f32_e32 v36, v42, v42
	v_fmac_f32_e32 v36, v43, v43
	v_fmac_f32_e32 v49, v46, v46
	v_fmac_f32_e32 v36, v44, v44
	v_cvt_pk_bf16_f32 v55, v46, v47
	v_fmac_f32_e32 v49, v47, v47
	v_pk_add_f32 v[46:47], v[38:39], v[102:103]
	v_fmac_f32_e32 v36, v45, v45
	v_fmac_f32_e32 v36, v46, v46
	v_fmac_f32_e32 v36, v47, v47
	v_add_f32_e32 v36, v49, v36
	v_mov_b32_e32 v37, v36
	s_nop 1
	v_permlane16_swap_b32_e32 v36, v37
	v_lshlrev_b64 v[58:59], 12, v[130:131]
	v_lshl_add_u64 v[58:59], s[8:9], 0, v[58:59]
	v_cvt_pk_bf16_f32 v53, v50, v51
	v_lshl_add_u64 v[58:59], v[202:203], 1, v[58:59]
	s_waitcnt lgkmcnt(0)
	v_add_f32_e32 v36, v36, v37
	v_mov_b32_e32 v37, v36
	s_nop 1
	v_permlane32_swap_b32_e32 v36, v37
	global_store_dwordx4 v[58:59], v[52:55], off
	global_store_dwordx4 v[56:57], v[40:43], off offset:512
	global_store_dwordx4 v[56:57], v[44:47], off offset:528
	v_cvt_pk_bf16_f32 v38, v40, v41
	v_cvt_pk_bf16_f32 v39, v42, v43
	s_nop 0
	v_cvt_pk_bf16_f32 v40, v44, v45
	v_cvt_pk_bf16_f32 v41, v46, v47
	global_store_dwordx4 v[58:59], v[38:41], off offset:256
	s_and_saveexec_b64 s[22:23], s[4:5]
	s_cbranch_execz .LBB0_635
	s_waitcnt lgkmcnt(0)
	v_add_f32_e32 v38, v36, v37
	v_lshl_add_u64 v[36:37], v[130:131], 2, s[12:13]
	global_atomic_add_f32 v[36:37], v38, off
; __device__ __forceinline__ float shx(float v, int mask, int lane) { return __int_as_float(__builtin_amdgcn_ds_bpermute((lane ^ mask) << 2, __float_as_int(v))); }
; __device__ __forceinline__ u32x4 pack8(const f32x4& a, const f32x4& b) { u32x4 w; w.x = pack2(a[0], a[1]); w.y = pack2(a[2], a[3]); w.z = pack2(b[0], b[1]); w.w = pack2(b[2], b[3]); return w; }
;     __device__ __forceinline__ void operator()(AccT& acc, const pg8::Unit& u, int wr, int wc, int fr, int fq, const LAS float* rs) const {
;     ...
;         for (int ai = 0; ai < 2; ++ai) {
;             f32x4 hv[4][2][2];
; #pragma unroll
;             for (int m = 0; m < 4; ++m)
; #pragma unroll
;                 for (int bj = 0; bj < 2; ++bj) { const float* hp = h + (size_t)(row0 + ai * 128 + m * 16) * D + cb + bj * 128; hv[m][bj][0] = *(const f32x4*)hp; hv[m][bj][1] = *(const f32x4*)(hp + 4); }
; #pragma unroll
;             for (int m = 0; m < 4; ++m) {
;                 const int row = row0 + ai * 128 + m * 16; float ss = 0.f;
; #pragma unroll
;                 for (int bj = 0; bj < 2; ++bj) {
;                     const int col = cb + bj * 128; float* hp = h + (size_t)row * D + col;
;                     const f32x4 o0 = hv[m][bj][0] + acc[ai][bj][m][0], o1 = hv[m][bj][1] + acc[ai][bj][m][1];
;                     *(f32x4*)hp = o0; *(f32x4*)(hp + 4) = o1;
;                     *(u32x4*)(hb + (size_t)row * D + col) = pack8(o0, o1);
;                     ss += o0[0] * o0[0] + o0[1] * o0[1] + o0[2] * o0[2] + o0[3] * o0[3] + o1[0] * o1[0] + o1[1] * o1[1] + o1[2] * o1[2] + o1[3] * o1[3];
;                 }
;                 ss += shx(ss, 16, lane); ss += shx(ss, 32, lane);
;                 if (fq == 0) atomicAdd(rsqn + row, ss);
;             }
.LBB0_635:
	s_or_b64 exec, exec, s[22:23]
	s_waitcnt lgkmcnt(0)
	v_lshl_add_u64 v[36:37], s[10:11], 0, v[132:133]
	v_lshl_add_u64 v[40:41], v[202:203], 2, v[36:37]
	s_waitcnt vmcnt(18)
	v_pk_add_f32 v[34:35], v[34:35], v[98:99]
	v_pk_add_f32 v[32:33], v[32:33], v[96:97]
	v_pk_add_f32 v[30:31], v[30:31], v[94:95]
	v_pk_add_f32 v[28:29], v[28:29], v[92:93]
	global_store_dwordx4 v[40:41], v[32:35], off
	global_store_dwordx4 v[40:41], v[28:31], off offset:16
	v_cvt_pk_bf16_f32 v36, v32, v33
	s_waitcnt vmcnt(18)
	v_pk_add_f32 v[24:25], v[24:25], v[84:85]
	v_mul_f32_e32 v33, v33, v33
	v_fmac_f32_e32 v33, v32, v32
	v_fmac_f32_e32 v33, v34, v34
	v_fmac_f32_e32 v33, v35, v35
	v_fmac_f32_e32 v33, v28, v28
	v_cvt_pk_bf16_f32 v38, v28, v29
	v_fmac_f32_e32 v33, v29, v29
	v_pk_add_f32 v[28:29], v[20:21], v[76:77]
	v_mul_f32_e32 v20, v25, v25
	v_pk_add_f32 v[26:27], v[26:27], v[86:87]
	v_fmac_f32_e32 v20, v24, v24
	v_fmac_f32_e32 v20, v26, v26
	v_fmac_f32_e32 v20, v27, v27
	v_fmac_f32_e32 v33, v30, v30
	v_fmac_f32_e32 v20, v28, v28
	v_cvt_pk_bf16_f32 v39, v30, v31
	v_fmac_f32_e32 v33, v31, v31
	v_pk_add_f32 v[30:31], v[22:23], v[78:79]
	v_fmac_f32_e32 v20, v29, v29
	v_fmac_f32_e32 v20, v30, v30
	v_fmac_f32_e32 v20, v31, v31
	v_add_f32_e32 v20, v33, v20
	v_mov_b32_e32 v21, v20
	s_nop 1
	v_permlane16_swap_b32_e32 v20, v21
	v_lshlrev_b64 v[42:43], 12, v[126:127]
	v_lshl_add_u64 v[42:43], s[8:9], 0, v[42:43]
	v_cvt_pk_bf16_f32 v37, v34, v35
	v_lshl_add_u64 v[42:43], v[202:203], 1, v[42:43]
	s_waitcnt lgkmcnt(0)
	v_add_f32_e32 v20, v20, v21
	v_mov_b32_e32 v21, v20
	s_nop 1
	v_permlane32_swap_b32_e32 v20, v21
	global_store_dwordx4 v[42:43], v[36:39], off
	global_store_dwordx4 v[40:41], v[24:27], off offset:512
	global_store_dwordx4 v[40:41], v[28:31], off offset:528
	v_cvt_pk_bf16_f32 v22, v24, v25
	v_cvt_pk_bf16_f32 v23, v26, v27
	s_nop 0
	v_cvt_pk_bf16_f32 v24, v28, v29
	v_cvt_pk_bf16_f32 v25, v30, v31
	global_store_dwordx4 v[42:43], v[22:25], off offset:256
	s_and_saveexec_b64 s[22:23], s[4:5]
	s_cbranch_execz .LBB0_637
	s_waitcnt lgkmcnt(0)
	v_add_f32_e32 v22, v20, v21
	v_lshl_add_u64 v[20:21], v[126:127], 2, s[12:13]
	global_atomic_add_f32 v[20:21], v22, off
.LBB0_637:
	s_or_b64 exec, exec, s[22:23]
	s_waitcnt lgkmcnt(0)
	v_lshl_add_u64 v[20:21], s[10:11], 0, v[128:129]
	v_lshl_add_u64 v[24:25], v[202:203], 2, v[20:21]
	s_waitcnt vmcnt(20)
	v_pk_add_f32 v[18:19], v[18:19], v[90:91]
	v_pk_add_f32 v[16:17], v[16:17], v[88:89]
	v_pk_add_f32 v[14:15], v[14:15], v[82:83]
	v_pk_add_f32 v[12:13], v[12:13], v[80:81]
	global_store_dwordx4 v[24:25], v[16:19], off
	global_store_dwordx4 v[24:25], v[12:15], off offset:16
	v_cvt_pk_bf16_f32 v20, v16, v17
	s_waitcnt vmcnt(20)
	v_pk_add_f32 v[8:9], v[8:9], v[72:73]
	v_mul_f32_e32 v17, v17, v17
	v_fmac_f32_e32 v17, v16, v16
	v_fmac_f32_e32 v17, v18, v18
	v_fmac_f32_e32 v17, v19, v19
	v_fmac_f32_e32 v17, v12, v12
	v_cvt_pk_bf16_f32 v22, v12, v13
	v_fmac_f32_e32 v17, v13, v13
	v_pk_add_f32 v[12:13], v[4:5], v[68:69]
	v_mul_f32_e32 v4, v9, v9
	v_pk_add_f32 v[10:11], v[10:11], v[74:75]
	v_fmac_f32_e32 v4, v8, v8
	v_fmac_f32_e32 v4, v10, v10
	v_fmac_f32_e32 v4, v11, v11
	v_fmac_f32_e32 v17, v14, v14
	v_fmac_f32_e32 v4, v12, v12
	v_cvt_pk_bf16_f32 v23, v14, v15
	v_fmac_f32_e32 v17, v15, v15
	v_pk_add_f32 v[14:15], v[6:7], v[70:71]
	v_fmac_f32_e32 v4, v13, v13
	v_fmac_f32_e32 v4, v14, v14
	v_fmac_f32_e32 v4, v15, v15
	v_add_f32_e32 v4, v17, v4
	v_mov_b32_e32 v5, v4
	s_nop 1
	v_permlane16_swap_b32_e32 v4, v5
	v_lshlrev_b64 v[26:27], 12, v[124:125]
	v_lshl_add_u64 v[26:27], s[8:9], 0, v[26:27]
	v_cvt_pk_bf16_f32 v21, v18, v19
	v_lshl_add_u64 v[26:27], v[202:203], 1, v[26:27]
	s_waitcnt lgkmcnt(0)
	v_add_f32_e32 v4, v4, v5
	v_mov_b32_e32 v5, v4
	s_nop 1
	v_permlane32_swap_b32_e32 v4, v5
	global_store_dwordx4 v[26:27], v[20:23], off
	global_store_dwordx4 v[24:25], v[8:11], off offset:512
	global_store_dwordx4 v[24:25], v[12:15], off offset:528
	v_cvt_pk_bf16_f32 v6, v8, v9
	v_cvt_pk_bf16_f32 v7, v10, v11
	s_nop 0
	v_cvt_pk_bf16_f32 v8, v12, v13
	v_cvt_pk_bf16_f32 v9, v14, v15
	global_store_dwordx4 v[26:27], v[6:9], off offset:256
	s_and_saveexec_b64 s[22:23], s[4:5]
	s_cbranch_execz .LBB0_618
	s_waitcnt lgkmcnt(0)
	v_add_f32_e32 v6, v4, v5
	v_lshl_add_u64 v[4:5], v[124:125], 2, s[12:13]
	global_atomic_add_f32 v[4:5], v6, off
	s_branch .LBB0_618

; #define LAS __attribute__((address_space(3)))
; __device__ __forceinline__ float shx(float v, int mask, int lane) { return __int_as_float(__builtin_amdgcn_ds_bpermute((lane ^ mask) << 2, __float_as_int(v))); }
; __device__ __forceinline__ u32x4 pack8(const f32x4& a, const f32x4& b) { u32x4 w; w.x = pack2(a[0], a[1]); w.y = pack2(a[2], a[3]); w.z = pack2(b[0], b[1]); w.w = pack2(b[2], b[3]); return w; }
;     __device__ __forceinline__ void operator()(AccT& acc, const pg8::Unit& u, int wr, int wc, int fr, int fq, const LAS float* rs) const {
;         int row0 = u.pm * 256 + wr * 64 + fr; asm volatile("" : "+v"(row0)); const int cb = u.pn * 256 + wc * 32 + 8 * fq, lane = fr + 16 * fq;
; #pragma unroll
;         for (int ai = 0; ai < 2; ++ai) {
;             f32x4 hv[4][2][2];
; #pragma unroll
;             for (int m = 0; m < 4; ++m)
; #pragma unroll
;                 for (int bj = 0; bj < 2; ++bj) { const float* hp = h + (size_t)(row0 + ai * 128 + m * 16) * D + cb + bj * 128; hv[m][bj][0] = *(const f32x4*)hp; hv[m][bj][1] = *(const f32x4*)(hp + 4); }
; #pragma unroll
;             for (int m = 0; m < 4; ++m) {
;                 const int row = row0 + ai * 128 + m * 16; float ss = 0.f;
; #pragma unroll
;                 for (int bj = 0; bj < 2; ++bj) {
;                     const int col = cb + bj * 128; float* hp = h + (size_t)row * D + col;
;                     const f32x4 o0 = hv[m][bj][0] + acc[ai][bj][m][0], o1 = hv[m][bj][1] + acc[ai][bj][m][1];
;                     *(f32x4*)hp = o0; *(f32x4*)(hp + 4) = o1;
;                     *(u32x4*)(hb + (size_t)row * D + col) = pack8(o0, o1);
;                     ss += o0[0] * o0[0] + o0[1] * o0[1] + o0[2] * o0[2] + o0[3] * o0[3] + o1[0] * o1[0] + o1[1] * o1[1] + o1[2] * o1[2] + o1[3] * o1[3];
;                 }
;                 ss += shx(ss, 16, lane); ss += shx(ss, 32, lane);
;                 if (fq == 0) atomicAdd(rsqn + row, ss);
;             }
;         }
;     }
.Ldn_epi:
	v_lshl_or_b32 v202, s45, 8, v233
	v_lshl_add_u32 v206, s46, 8, v197
	v_ashrrev_i32_e32 v203, 31, v202
	v_lshlrev_b64 v[244:245], 2, v[202:203]
	v_ashrrev_i32_e32 v207, 31, v206
	v_lshl_add_u64 v[204:205], s[14:15], 0, v[244:245]
	v_lshlrev_b64 v[246:247], 13, v[206:207]
	v_lshl_add_u64 v[132:133], v[204:205], 0, v[246:247]
	global_load_dwordx4 v[236:239], v[132:133], off offset:16
	global_load_dwordx4 v[240:243], v[132:133], off
	global_load_dwordx4 v[180:183], v[132:133], off offset:528
	global_load_dwordx4 v[184:187], v[132:133], off offset:512
	v_add_u32_e32 v214, 16, v206
	v_ashrrev_i32_e32 v215, 31, v214
	v_add_u32_e32 v210, 32, v206
	v_add_u32_e32 v208, 48, v206
	v_lshlrev_b64 v[218:219], 13, v[214:215]
	v_ashrrev_i32_e32 v211, 31, v210
	v_ashrrev_i32_e32 v209, 31, v208
	v_lshl_add_u64 v[132:133], v[204:205], 0, v[218:219]
	v_lshlrev_b64 v[216:217], 13, v[210:211]
	v_lshlrev_b64 v[212:213], 13, v[208:209]
	global_load_dwordx4 v[172:175], v[132:133], off offset:16
	global_load_dwordx4 v[176:179], v[132:133], off
	global_load_dwordx4 v[164:167], v[132:133], off offset:528
	global_load_dwordx4 v[168:171], v[132:133], off offset:512
	v_lshl_add_u64 v[132:133], v[204:205], 0, v[216:217]
	v_lshl_add_u64 v[136:137], v[204:205], 0, v[212:213]
	global_load_dwordx4 v[156:159], v[132:133], off offset:16
	global_load_dwordx4 v[160:163], v[132:133], off
	global_load_dwordx4 v[140:143], v[132:133], off offset:528
	global_load_dwordx4 v[148:151], v[132:133], off offset:512
	global_load_dwordx4 v[144:147], v[136:137], off offset:16
	global_load_dwordx4 v[152:155], v[136:137], off
	s_nop 0
	global_load_dwordx4 v[132:135], v[136:137], off offset:528
	s_nop 0
	global_load_dwordx4 v[136:139], v[136:137], off offset:512
	v_lshl_add_u64 v[246:247], s[14:15], 0, v[246:247]
	v_lshl_add_u64 v[244:245], v[246:247], 0, v[244:245]
	s_waitcnt vmcnt(0)
	v_pk_add_f32 v[126:127], v[126:127], v[238:239]
	v_pk_add_f32 v[130:131], v[130:131], v[242:243]
	v_pk_add_f32 v[128:129], v[128:129], v[240:241]
	v_pk_add_f32 v[124:125], v[124:125], v[236:237]
	global_store_dwordx4 v[244:245], v[128:131], off
	global_store_dwordx4 v[244:245], v[124:127], off offset:16
	v_cvt_pk_bf16_f32 v236, v128, v129
	v_lshlrev_b64 v[240:241], 12, v[206:207]
	v_mul_f32_e32 v129, v129, v129
	v_fmac_f32_e32 v129, v128, v128
	v_lshl_add_u64 v[240:241], s[12:13], 0, v[240:241]
	v_fmac_f32_e32 v129, v130, v130
	v_lshl_add_u64 v[240:241], v[202:203], 1, v[240:241]
	v_fmac_f32_e32 v129, v131, v131
	v_pk_add_f32 v[122:123], v[122:123], v[186:187]
	v_pk_add_f32 v[120:121], v[120:121], v[184:185]
	v_cvt_pk_bf16_f32 v237, v130, v131
	v_cvt_pk_bf16_f32 v238, v124, v125
	v_cvt_pk_bf16_f32 v239, v126, v127
	global_store_dwordx4 v[240:241], v[236:239], off
	v_fmac_f32_e32 v129, v124, v124
	v_pk_add_f32 v[118:119], v[118:119], v[182:183]
	v_pk_add_f32 v[116:117], v[116:117], v[180:181]
	global_store_dwordx4 v[244:245], v[120:123], off offset:512
	global_store_dwordx4 v[244:245], v[116:119], off offset:528
	v_cvt_pk_bf16_f32 v124, v120, v121
	v_fmac_f32_e32 v129, v125, v125
	v_mul_f32_e32 v121, v121, v121
	v_fmac_f32_e32 v121, v120, v120
	v_fmac_f32_e32 v121, v122, v122
	v_fmac_f32_e32 v121, v123, v123
	v_fmac_f32_e32 v121, v116, v116
	v_fmac_f32_e32 v121, v117, v117
	v_fmac_f32_e32 v129, v126, v126
	v_fmac_f32_e32 v121, v118, v118
	v_fmac_f32_e32 v129, v127, v127
	v_fmac_f32_e32 v121, v119, v119
	v_cvt_pk_bf16_f32 v126, v116, v117
	v_add_f32_e32 v116, v129, v121
	v_mov_b32_e32 v117, v116
	s_nop 1
	v_permlane16_swap_b32_e32 v116, v117
	v_cvt_pk_bf16_f32 v125, v122, v123
	v_cvt_pk_bf16_f32 v127, v118, v119
	global_store_dwordx4 v[240:241], v[124:127], off offset:256
	s_waitcnt lgkmcnt(0)
	v_add_f32_e32 v116, v116, v117
	v_mov_b32_e32 v117, v116
	s_nop 1
	v_permlane32_swap_b32_e32 v116, v117
	s_and_saveexec_b64 s[18:19], s[4:5]
	s_cbranch_execz .LBB0_928
	s_waitcnt lgkmcnt(0)
	v_add_f32_e32 v118, v116, v117
	v_lshl_add_u64 v[116:117], v[206:207], 2, s[16:17]
	global_atomic_add_f32 v[116:117], v118, off
.LBB0_928:
	s_or_b64 exec, exec, s[18:19]
	s_waitcnt lgkmcnt(0)
	v_lshl_add_u64 v[116:117], s[14:15], 0, v[218:219]
	v_lshl_add_u64 v[120:121], v[202:203], 2, v[116:117]
	v_pk_add_f32 v[114:115], v[114:115], v[178:179]
	v_pk_add_f32 v[112:113], v[112:113], v[176:177]
	v_pk_add_f32 v[110:111], v[110:111], v[174:175]
	v_pk_add_f32 v[108:109], v[108:109], v[172:173]
	global_store_dwordx4 v[120:121], v[112:115], off
	global_store_dwordx4 v[120:121], v[108:111], off offset:16
	v_cvt_pk_bf16_f32 v116, v112, v113
	v_pk_add_f32 v[104:105], v[104:105], v[168:169]
	v_mul_f32_e32 v113, v113, v113
	v_fmac_f32_e32 v113, v112, v112
	v_fmac_f32_e32 v113, v114, v114
	v_fmac_f32_e32 v113, v115, v115
	v_fmac_f32_e32 v113, v108, v108
	v_cvt_pk_bf16_f32 v118, v108, v109
	v_fmac_f32_e32 v113, v109, v109
	v_pk_add_f32 v[108:109], v[100:101], v[164:165]
	v_mul_f32_e32 v100, v105, v105
	v_pk_add_f32 v[106:107], v[106:107], v[170:171]
	v_fmac_f32_e32 v100, v104, v104
	v_fmac_f32_e32 v100, v106, v106
	v_fmac_f32_e32 v100, v107, v107
	v_fmac_f32_e32 v113, v110, v110
	v_fmac_f32_e32 v100, v108, v108
	v_cvt_pk_bf16_f32 v119, v110, v111
	v_fmac_f32_e32 v113, v111, v111
	v_pk_add_f32 v[110:111], v[102:103], v[166:167]
	v_fmac_f32_e32 v100, v109, v109
	v_fmac_f32_e32 v100, v110, v110
	v_fmac_f32_e32 v100, v111, v111
	v_add_f32_e32 v100, v113, v100
	v_mov_b32_e32 v101, v100
	s_nop 1
	v_permlane16_swap_b32_e32 v100, v101
	v_lshlrev_b64 v[122:123], 12, v[214:215]
	v_lshl_add_u64 v[122:123], s[12:13], 0, v[122:123]
	v_cvt_pk_bf16_f32 v117, v114, v115
	v_lshl_add_u64 v[122:123], v[202:203], 1, v[122:123]
	s_waitcnt lgkmcnt(0)
	v_add_f32_e32 v100, v100, v101
	v_mov_b32_e32 v101, v100
	s_nop 1
	v_permlane32_swap_b32_e32 v100, v101
	global_store_dwordx4 v[122:123], v[116:119], off
	global_store_dwordx4 v[120:121], v[104:107], off offset:512
	global_store_dwordx4 v[120:121], v[108:111], off offset:528
	v_cvt_pk_bf16_f32 v102, v104, v105
	v_cvt_pk_bf16_f32 v103, v106, v107
	s_nop 0
	v_cvt_pk_bf16_f32 v104, v108, v109
	v_cvt_pk_bf16_f32 v105, v110, v111
	global_store_dwordx4 v[122:123], v[102:105], off offset:256
	s_and_saveexec_b64 s[18:19], s[4:5]
	s_cbranch_execz .LBB0_930
	s_waitcnt lgkmcnt(0)
	v_add_f32_e32 v102, v100, v101
	v_lshl_add_u64 v[100:101], v[214:215], 2, s[16:17]
	global_atomic_add_f32 v[100:101], v102, off
; __device__ __forceinline__ float shx(float v, int mask, int lane) { return __int_as_float(__builtin_amdgcn_ds_bpermute((lane ^ mask) << 2, __float_as_int(v))); }
; __device__ __forceinline__ u32x4 pack8(const f32x4& a, const f32x4& b) { u32x4 w; w.x = pack2(a[0], a[1]); w.y = pack2(a[2], a[3]); w.z = pack2(b[0], b[1]); w.w = pack2(b[2], b[3]); return w; }
;     __device__ __forceinline__ void operator()(AccT& acc, const pg8::Unit& u, int wr, int wc, int fr, int fq, const LAS float* rs) const {
;     ...
;         for (int ai = 0; ai < 2; ++ai) {
;             f32x4 hv[4][2][2];
; #pragma unroll
;             for (int m = 0; m < 4; ++m)
; #pragma unroll
;                 for (int bj = 0; bj < 2; ++bj) { const float* hp = h + (size_t)(row0 + ai * 128 + m * 16) * D + cb + bj * 128; hv[m][bj][0] = *(const f32x4*)hp; hv[m][bj][1] = *(const f32x4*)(hp + 4); }
; #pragma unroll
;             for (int m = 0; m < 4; ++m) {
;                 const int row = row0 + ai * 128 + m * 16; float ss = 0.f;
; #pragma unroll
;                 for (int bj = 0; bj < 2; ++bj) {
;                     const int col = cb + bj * 128; float* hp = h + (size_t)row * D + col;
;                     const f32x4 o0 = hv[m][bj][0] + acc[ai][bj][m][0], o1 = hv[m][bj][1] + acc[ai][bj][m][1];
;                     *(f32x4*)hp = o0; *(f32x4*)(hp + 4) = o1;
;                     *(u32x4*)(hb + (size_t)row * D + col) = pack8(o0, o1);
;                     ss += o0[0] * o0[0] + o0[1] * o0[1] + o0[2] * o0[2] + o0[3] * o0[3] + o1[0] * o1[0] + o1[1] * o1[1] + o1[2] * o1[2] + o1[3] * o1[3];
;                 }
;                 ss += shx(ss, 16, lane); ss += shx(ss, 32, lane);
;                 if (fq == 0) atomicAdd(rsqn + row, ss);
;             }
.LBB0_930:
	s_or_b64 exec, exec, s[18:19]
	s_waitcnt lgkmcnt(0)
	v_lshl_add_u64 v[100:101], s[14:15], 0, v[216:217]
	v_lshl_add_u64 v[104:105], v[202:203], 2, v[100:101]
	v_pk_add_f32 v[98:99], v[98:99], v[162:163]
	v_pk_add_f32 v[96:97], v[96:97], v[160:161]
	v_pk_add_f32 v[94:95], v[94:95], v[158:159]
	v_pk_add_f32 v[92:93], v[92:93], v[156:157]
	global_store_dwordx4 v[104:105], v[96:99], off
	global_store_dwordx4 v[104:105], v[92:95], off offset:16
	v_cvt_pk_bf16_f32 v100, v96, v97
	v_pk_add_f32 v[88:89], v[88:89], v[148:149]
	v_mul_f32_e32 v97, v97, v97
	v_fmac_f32_e32 v97, v96, v96
	v_fmac_f32_e32 v97, v98, v98
	v_fmac_f32_e32 v97, v99, v99
	v_fmac_f32_e32 v97, v92, v92
	v_cvt_pk_bf16_f32 v102, v92, v93
	v_fmac_f32_e32 v97, v93, v93
	v_pk_add_f32 v[92:93], v[84:85], v[140:141]
	v_mul_f32_e32 v84, v89, v89
	v_pk_add_f32 v[90:91], v[90:91], v[150:151]
	v_fmac_f32_e32 v84, v88, v88
	v_fmac_f32_e32 v84, v90, v90
	v_fmac_f32_e32 v84, v91, v91
	v_fmac_f32_e32 v97, v94, v94
	v_fmac_f32_e32 v84, v92, v92
	v_cvt_pk_bf16_f32 v103, v94, v95
	v_fmac_f32_e32 v97, v95, v95
	v_pk_add_f32 v[94:95], v[86:87], v[142:143]
	v_fmac_f32_e32 v84, v93, v93
	v_fmac_f32_e32 v84, v94, v94
	v_fmac_f32_e32 v84, v95, v95
	v_add_f32_e32 v84, v97, v84
	v_mov_b32_e32 v85, v84
	s_nop 1
	v_permlane16_swap_b32_e32 v84, v85
	v_lshlrev_b64 v[106:107], 12, v[210:211]
	v_lshl_add_u64 v[106:107], s[12:13], 0, v[106:107]
	v_cvt_pk_bf16_f32 v101, v98, v99
	v_lshl_add_u64 v[106:107], v[202:203], 1, v[106:107]
	s_waitcnt lgkmcnt(0)
	v_add_f32_e32 v84, v84, v85
	v_mov_b32_e32 v85, v84
	s_nop 1
	v_permlane32_swap_b32_e32 v84, v85
	global_store_dwordx4 v[106:107], v[100:103], off
	global_store_dwordx4 v[104:105], v[88:91], off offset:512
	global_store_dwordx4 v[104:105], v[92:95], off offset:528
	v_cvt_pk_bf16_f32 v86, v88, v89
	v_cvt_pk_bf16_f32 v87, v90, v91
	s_nop 0
	v_cvt_pk_bf16_f32 v88, v92, v93
	v_cvt_pk_bf16_f32 v89, v94, v95
	global_store_dwordx4 v[106:107], v[86:89], off offset:256
	s_and_saveexec_b64 s[18:19], s[4:5]
	s_cbranch_execz .LBB0_932
	s_waitcnt lgkmcnt(0)
	v_add_f32_e32 v86, v84, v85
	v_lshl_add_u64 v[84:85], v[210:211], 2, s[16:17]
	global_atomic_add_f32 v[84:85], v86, off
.LBB0_932:
	s_or_b64 exec, exec, s[18:19]
	s_waitcnt lgkmcnt(0)
	v_lshl_add_u64 v[84:85], s[14:15], 0, v[212:213]
	v_lshl_add_u64 v[88:89], v[202:203], 2, v[84:85]
	v_pk_add_f32 v[82:83], v[82:83], v[154:155]
	v_pk_add_f32 v[80:81], v[80:81], v[152:153]
	v_pk_add_f32 v[78:79], v[78:79], v[146:147]
	v_pk_add_f32 v[76:77], v[76:77], v[144:145]
	global_store_dwordx4 v[88:89], v[80:83], off
	global_store_dwordx4 v[88:89], v[76:79], off offset:16
	v_cvt_pk_bf16_f32 v84, v80, v81
	v_pk_add_f32 v[72:73], v[72:73], v[136:137]
	v_mul_f32_e32 v81, v81, v81
	v_fmac_f32_e32 v81, v80, v80
	v_fmac_f32_e32 v81, v82, v82
	v_fmac_f32_e32 v81, v83, v83
	v_fmac_f32_e32 v81, v76, v76
	v_cvt_pk_bf16_f32 v86, v76, v77
	v_fmac_f32_e32 v81, v77, v77
	v_pk_add_f32 v[76:77], v[68:69], v[132:133]
	v_mul_f32_e32 v68, v73, v73
	v_pk_add_f32 v[74:75], v[74:75], v[138:139]
	v_fmac_f32_e32 v68, v72, v72
	v_fmac_f32_e32 v68, v74, v74
	v_fmac_f32_e32 v68, v75, v75
	v_fmac_f32_e32 v81, v78, v78
	v_fmac_f32_e32 v68, v76, v76
	v_cvt_pk_bf16_f32 v87, v78, v79
	v_fmac_f32_e32 v81, v79, v79
	v_pk_add_f32 v[78:79], v[70:71], v[134:135]
	v_fmac_f32_e32 v68, v77, v77
	v_fmac_f32_e32 v68, v78, v78
	v_fmac_f32_e32 v68, v79, v79
	v_add_f32_e32 v68, v81, v68
	v_mov_b32_e32 v69, v68
	s_nop 1
	v_permlane16_swap_b32_e32 v68, v69
	v_lshlrev_b64 v[90:91], 12, v[208:209]
	v_lshl_add_u64 v[90:91], s[12:13], 0, v[90:91]
	v_cvt_pk_bf16_f32 v85, v82, v83
	v_lshl_add_u64 v[90:91], v[202:203], 1, v[90:91]
	s_waitcnt lgkmcnt(0)
	v_add_f32_e32 v68, v68, v69
	v_mov_b32_e32 v69, v68
	s_nop 1
	v_permlane32_swap_b32_e32 v68, v69
	global_store_dwordx4 v[90:91], v[84:87], off
	global_store_dwordx4 v[88:89], v[72:75], off offset:512
	global_store_dwordx4 v[88:89], v[76:79], off offset:528
	v_cvt_pk_bf16_f32 v70, v72, v73
	v_cvt_pk_bf16_f32 v71, v74, v75
	s_nop 0
	v_cvt_pk_bf16_f32 v72, v76, v77
	v_cvt_pk_bf16_f32 v73, v78, v79
	global_store_dwordx4 v[90:91], v[70:73], off offset:256
	s_and_saveexec_b64 s[18:19], s[4:5]
	s_cbranch_execz .LBB0_934
	s_waitcnt lgkmcnt(0)
	v_add_f32_e32 v70, v68, v69
	v_lshl_add_u64 v[68:69], v[208:209], 2, s[16:17]
	global_atomic_add_f32 v[68:69], v70, off
; __device__ __forceinline__ float shx(float v, int mask, int lane) { return __int_as_float(__builtin_amdgcn_ds_bpermute((lane ^ mask) << 2, __float_as_int(v))); }
; __device__ __forceinline__ u32x4 pack8(const f32x4& a, const f32x4& b) { u32x4 w; w.x = pack2(a[0], a[1]); w.y = pack2(a[2], a[3]); w.z = pack2(b[0], b[1]); w.w = pack2(b[2], b[3]); return w; }
;     __device__ __forceinline__ void operator()(AccT& acc, const pg8::Unit& u, int wr, int wc, int fr, int fq, const LAS float* rs) const {
;     ...
;         for (int ai = 0; ai < 2; ++ai) {
;             f32x4 hv[4][2][2];
; #pragma unroll
;             for (int m = 0; m < 4; ++m)
; #pragma unroll
;                 for (int bj = 0; bj < 2; ++bj) { const float* hp = h + (size_t)(row0 + ai * 128 + m * 16) * D + cb + bj * 128; hv[m][bj][0] = *(const f32x4*)hp; hv[m][bj][1] = *(const f32x4*)(hp + 4); }
; #pragma unroll
;             for (int m = 0; m < 4; ++m) {
;                 const int row = row0 + ai * 128 + m * 16; float ss = 0.f;
; #pragma unroll
;                 for (int bj = 0; bj < 2; ++bj) {
;                     const int col = cb + bj * 128; float* hp = h + (size_t)row * D + col;
;                     const f32x4 o0 = hv[m][bj][0] + acc[ai][bj][m][0], o1 = hv[m][bj][1] + acc[ai][bj][m][1];
;                     *(f32x4*)hp = o0; *(f32x4*)(hp + 4) = o1;
;                     *(u32x4*)(hb + (size_t)row * D + col) = pack8(o0, o1);
;                     ss += o0[0] * o0[0] + o0[1] * o0[1] + o0[2] * o0[2] + o0[3] * o0[3] + o1[0] * o1[0] + o1[1] * o1[1] + o1[2] * o1[2] + o1[3] * o1[3];
;                 }
;                 ss += shx(ss, 16, lane); ss += shx(ss, 32, lane);
;                 if (fq == 0) atomicAdd(rsqn + row, ss);
;             }
.LBB0_934:
	s_or_b64 exec, exec, s[18:19]
	v_add_u32_e32 v134, 0x80, v206
	v_ashrrev_i32_e32 v135, 31, v134
	v_lshlrev_b64 v[146:147], 13, v[134:135]
	s_waitcnt lgkmcnt(0)
	v_lshl_add_u64 v[68:69], v[204:205], 0, v[146:147]
	global_load_dwordx4 v[138:141], v[68:69], off offset:16
	global_load_dwordx4 v[142:145], v[68:69], off
	global_load_dwordx4 v[116:119], v[68:69], off offset:528
	global_load_dwordx4 v[120:123], v[68:69], off offset:512
	v_add_u32_e32 v130, 0x90, v206
	v_ashrrev_i32_e32 v131, 31, v130
	v_add_u32_e32 v126, 0xa0, v206
	v_add_u32_e32 v124, 0xb0, v206
	v_lshlrev_b64 v[136:137], 13, v[130:131]
	v_ashrrev_i32_e32 v127, 31, v126
	v_ashrrev_i32_e32 v125, 31, v124
	v_lshl_add_u64 v[68:69], v[204:205], 0, v[136:137]
	v_lshlrev_b64 v[132:133], 13, v[126:127]
	v_lshlrev_b64 v[128:129], 13, v[124:125]
	global_load_dwordx4 v[108:111], v[68:69], off offset:16
	global_load_dwordx4 v[112:115], v[68:69], off
	global_load_dwordx4 v[100:103], v[68:69], off offset:528
	global_load_dwordx4 v[104:107], v[68:69], off offset:512
	v_lshl_add_u64 v[68:69], v[204:205], 0, v[132:133]
	v_lshl_add_u64 v[72:73], v[204:205], 0, v[128:129]
	global_load_dwordx4 v[92:95], v[68:69], off offset:16
	global_load_dwordx4 v[96:99], v[68:69], off
	global_load_dwordx4 v[76:79], v[68:69], off offset:528
	global_load_dwordx4 v[84:87], v[68:69], off offset:512
	global_load_dwordx4 v[80:83], v[72:73], off offset:16
	global_load_dwordx4 v[88:91], v[72:73], off
	s_nop 0
	global_load_dwordx4 v[68:71], v[72:73], off offset:528
	s_nop 0
	global_load_dwordx4 v[72:75], v[72:73], off offset:512
	v_lshl_add_u64 v[146:147], s[14:15], 0, v[146:147]
	v_lshl_add_u64 v[146:147], v[202:203], 2, v[146:147]
	s_waitcnt vmcnt(15)
	v_pk_add_f32 v[62:63], v[62:63], v[140:141]
	s_waitcnt vmcnt(14)
	v_pk_add_f32 v[66:67], v[66:67], v[144:145]
	v_pk_add_f32 v[64:65], v[64:65], v[142:143]
	v_pk_add_f32 v[60:61], v[60:61], v[138:139]
	global_store_dwordx4 v[146:147], v[64:67], off
	global_store_dwordx4 v[146:147], v[60:63], off offset:16
	v_cvt_pk_bf16_f32 v138, v64, v65
	v_lshlrev_b64 v[142:143], 12, v[134:135]
	v_mul_f32_e32 v65, v65, v65
	v_fmac_f32_e32 v65, v64, v64
	v_lshl_add_u64 v[142:143], s[12:13], 0, v[142:143]
	v_fmac_f32_e32 v65, v66, v66
	v_lshl_add_u64 v[142:143], v[202:203], 1, v[142:143]
	v_fmac_f32_e32 v65, v67, v67
	s_waitcnt vmcnt(14)
	v_pk_add_f32 v[58:59], v[58:59], v[122:123]
	v_pk_add_f32 v[56:57], v[56:57], v[120:121]
	v_cvt_pk_bf16_f32 v139, v66, v67
	v_cvt_pk_bf16_f32 v140, v60, v61
	v_cvt_pk_bf16_f32 v141, v62, v63
	global_store_dwordx4 v[142:143], v[138:141], off
	v_fmac_f32_e32 v65, v60, v60
	v_pk_add_f32 v[54:55], v[54:55], v[118:119]
	v_pk_add_f32 v[52:53], v[52:53], v[116:117]
	global_store_dwordx4 v[146:147], v[56:59], off offset:512
	global_store_dwordx4 v[146:147], v[52:55], off offset:528
	v_cvt_pk_bf16_f32 v60, v56, v57
	v_fmac_f32_e32 v65, v61, v61
	v_mul_f32_e32 v57, v57, v57
	v_fmac_f32_e32 v57, v56, v56
	v_fmac_f32_e32 v57, v58, v58
	v_fmac_f32_e32 v57, v59, v59
	v_fmac_f32_e32 v57, v52, v52
	v_fmac_f32_e32 v57, v53, v53
	v_fmac_f32_e32 v65, v62, v62
	v_fmac_f32_e32 v57, v54, v54
	v_fmac_f32_e32 v65, v63, v63
	v_fmac_f32_e32 v57, v55, v55
	v_cvt_pk_bf16_f32 v62, v52, v53
	v_add_f32_e32 v52, v65, v57
	v_mov_b32_e32 v53, v52
	s_nop 1
	v_permlane16_swap_b32_e32 v52, v53
	v_cvt_pk_bf16_f32 v61, v58, v59
	v_cvt_pk_bf16_f32 v63, v54, v55
	global_store_dwordx4 v[142:143], v[60:63], off offset:256
	s_waitcnt lgkmcnt(0)
	v_add_f32_e32 v52, v52, v53
	v_mov_b32_e32 v53, v52
	s_nop 1
	v_permlane32_swap_b32_e32 v52, v53
	s_and_saveexec_b64 s[18:19], s[4:5]
	s_cbranch_execz .LBB0_936
	s_waitcnt lgkmcnt(0)
	v_add_f32_e32 v54, v52, v53
	v_lshl_add_u64 v[52:53], v[134:135], 2, s[16:17]
	global_atomic_add_f32 v[52:53], v54, off
.LBB0_936:
	s_or_b64 exec, exec, s[18:19]
	s_waitcnt lgkmcnt(0)
	v_lshl_add_u64 v[52:53], s[14:15], 0, v[136:137]
	v_lshl_add_u64 v[56:57], v[202:203], 2, v[52:53]
	s_waitcnt vmcnt(16)
	v_pk_add_f32 v[50:51], v[50:51], v[114:115]
	v_pk_add_f32 v[48:49], v[48:49], v[112:113]
	v_pk_add_f32 v[46:47], v[46:47], v[110:111]
	v_pk_add_f32 v[44:45], v[44:45], v[108:109]
	global_store_dwordx4 v[56:57], v[48:51], off
	global_store_dwordx4 v[56:57], v[44:47], off offset:16
	v_cvt_pk_bf16_f32 v52, v48, v49
	s_waitcnt vmcnt(16)
	v_pk_add_f32 v[40:41], v[40:41], v[104:105]
	v_mul_f32_e32 v49, v49, v49
	v_fmac_f32_e32 v49, v48, v48
	v_fmac_f32_e32 v49, v50, v50
	v_fmac_f32_e32 v49, v51, v51
	v_fmac_f32_e32 v49, v44, v44
	v_cvt_pk_bf16_f32 v54, v44, v45
	v_fmac_f32_e32 v49, v45, v45
	v_pk_add_f32 v[44:45], v[36:37], v[100:101]
	v_mul_f32_e32 v36, v41, v41
	v_pk_add_f32 v[42:43], v[42:43], v[106:107]
	v_fmac_f32_e32 v36, v40, v40
	v_fmac_f32_e32 v36, v42, v42
	v_fmac_f32_e32 v36, v43, v43
	v_fmac_f32_e32 v49, v46, v46
	v_fmac_f32_e32 v36, v44, v44
	v_cvt_pk_bf16_f32 v55, v46, v47
	v_fmac_f32_e32 v49, v47, v47
	v_pk_add_f32 v[46:47], v[38:39], v[102:103]
	v_fmac_f32_e32 v36, v45, v45
	v_fmac_f32_e32 v36, v46, v46
	v_fmac_f32_e32 v36, v47, v47
	v_add_f32_e32 v36, v49, v36
	v_mov_b32_e32 v37, v36
	s_nop 1
	v_permlane16_swap_b32_e32 v36, v37
	v_lshlrev_b64 v[58:59], 12, v[130:131]
	v_lshl_add_u64 v[58:59], s[12:13], 0, v[58:59]
	v_cvt_pk_bf16_f32 v53, v50, v51
	v_lshl_add_u64 v[58:59], v[202:203], 1, v[58:59]
	s_waitcnt lgkmcnt(0)
	v_add_f32_e32 v36, v36, v37
	v_mov_b32_e32 v37, v36
	s_nop 1
	v_permlane32_swap_b32_e32 v36, v37
	global_store_dwordx4 v[58:59], v[52:55], off
	global_store_dwordx4 v[56:57], v[40:43], off offset:512
	global_store_dwordx4 v[56:57], v[44:47], off offset:528
	v_cvt_pk_bf16_f32 v38, v40, v41
	v_cvt_pk_bf16_f32 v39, v42, v43
	s_nop 0
	v_cvt_pk_bf16_f32 v40, v44, v45
	v_cvt_pk_bf16_f32 v41, v46, v47
	global_store_dwordx4 v[58:59], v[38:41], off offset:256
	s_and_saveexec_b64 s[18:19], s[4:5]
	s_cbranch_execz .LBB0_938
	s_waitcnt lgkmcnt(0)
	v_add_f32_e32 v38, v36, v37
	v_lshl_add_u64 v[36:37], v[130:131], 2, s[16:17]
	global_atomic_add_f32 v[36:37], v38, off
; __device__ __forceinline__ float shx(float v, int mask, int lane) { return __int_as_float(__builtin_amdgcn_ds_bpermute((lane ^ mask) << 2, __float_as_int(v))); }
; __device__ __forceinline__ u32x4 pack8(const f32x4& a, const f32x4& b) { u32x4 w; w.x = pack2(a[0], a[1]); w.y = pack2(a[2], a[3]); w.z = pack2(b[0], b[1]); w.w = pack2(b[2], b[3]); return w; }
;     __device__ __forceinline__ void operator()(AccT& acc, const pg8::Unit& u, int wr, int wc, int fr, int fq, const LAS float* rs) const {
;     ...
;         for (int ai = 0; ai < 2; ++ai) {
;             f32x4 hv[4][2][2];
; #pragma unroll
;             for (int m = 0; m < 4; ++m)
; #pragma unroll
;                 for (int bj = 0; bj < 2; ++bj) { const float* hp = h + (size_t)(row0 + ai * 128 + m * 16) * D + cb + bj * 128; hv[m][bj][0] = *(const f32x4*)hp; hv[m][bj][1] = *(const f32x4*)(hp + 4); }
; #pragma unroll
;             for (int m = 0; m < 4; ++m) {
;                 const int row = row0 + ai * 128 + m * 16; float ss = 0.f;
; #pragma unroll
;                 for (int bj = 0; bj < 2; ++bj) {
;                     const int col = cb + bj * 128; float* hp = h + (size_t)row * D + col;
;                     const f32x4 o0 = hv[m][bj][0] + acc[ai][bj][m][0], o1 = hv[m][bj][1] + acc[ai][bj][m][1];
;                     *(f32x4*)hp = o0; *(f32x4*)(hp + 4) = o1;
;                     *(u32x4*)(hb + (size_t)row * D + col) = pack8(o0, o1);
;                     ss += o0[0] * o0[0] + o0[1] * o0[1] + o0[2] * o0[2] + o0[3] * o0[3] + o1[0] * o1[0] + o1[1] * o1[1] + o1[2] * o1[2] + o1[3] * o1[3];
;                 }
;                 ss += shx(ss, 16, lane); ss += shx(ss, 32, lane);
;                 if (fq == 0) atomicAdd(rsqn + row, ss);
;             }
.LBB0_938:
	s_or_b64 exec, exec, s[18:19]
	s_waitcnt lgkmcnt(0)
	v_lshl_add_u64 v[36:37], s[14:15], 0, v[132:133]
	v_lshl_add_u64 v[40:41], v[202:203], 2, v[36:37]
	s_waitcnt vmcnt(18)
	v_pk_add_f32 v[34:35], v[34:35], v[98:99]
	v_pk_add_f32 v[32:33], v[32:33], v[96:97]
	v_pk_add_f32 v[30:31], v[30:31], v[94:95]
	v_pk_add_f32 v[28:29], v[28:29], v[92:93]
	global_store_dwordx4 v[40:41], v[32:35], off
	global_store_dwordx4 v[40:41], v[28:31], off offset:16
	v_cvt_pk_bf16_f32 v36, v32, v33
	s_waitcnt vmcnt(18)
	v_pk_add_f32 v[24:25], v[24:25], v[84:85]
	v_mul_f32_e32 v33, v33, v33
	v_fmac_f32_e32 v33, v32, v32
	v_fmac_f32_e32 v33, v34, v34
	v_fmac_f32_e32 v33, v35, v35
	v_fmac_f32_e32 v33, v28, v28
	v_cvt_pk_bf16_f32 v38, v28, v29
	v_fmac_f32_e32 v33, v29, v29
	v_pk_add_f32 v[28:29], v[20:21], v[76:77]
	v_mul_f32_e32 v20, v25, v25
	v_pk_add_f32 v[26:27], v[26:27], v[86:87]
	v_fmac_f32_e32 v20, v24, v24
	v_fmac_f32_e32 v20, v26, v26
	v_fmac_f32_e32 v20, v27, v27
	v_fmac_f32_e32 v33, v30, v30
	v_fmac_f32_e32 v20, v28, v28
	v_cvt_pk_bf16_f32 v39, v30, v31
	v_fmac_f32_e32 v33, v31, v31
	v_pk_add_f32 v[30:31], v[22:23], v[78:79]
	v_fmac_f32_e32 v20, v29, v29
	v_fmac_f32_e32 v20, v30, v30
	v_fmac_f32_e32 v20, v31, v31
	v_add_f32_e32 v20, v33, v20
	v_mov_b32_e32 v21, v20
	s_nop 1
	v_permlane16_swap_b32_e32 v20, v21
	v_lshlrev_b64 v[42:43], 12, v[126:127]
	v_lshl_add_u64 v[42:43], s[12:13], 0, v[42:43]
	v_cvt_pk_bf16_f32 v37, v34, v35
	v_lshl_add_u64 v[42:43], v[202:203], 1, v[42:43]
	s_waitcnt lgkmcnt(0)
	v_add_f32_e32 v20, v20, v21
	v_mov_b32_e32 v21, v20
	s_nop 1
	v_permlane32_swap_b32_e32 v20, v21
	global_store_dwordx4 v[42:43], v[36:39], off
	global_store_dwordx4 v[40:41], v[24:27], off offset:512
	global_store_dwordx4 v[40:41], v[28:31], off offset:528
	v_cvt_pk_bf16_f32 v22, v24, v25
	v_cvt_pk_bf16_f32 v23, v26, v27
	s_nop 0
	v_cvt_pk_bf16_f32 v24, v28, v29
	v_cvt_pk_bf16_f32 v25, v30, v31
	global_store_dwordx4 v[42:43], v[22:25], off offset:256
	s_and_saveexec_b64 s[18:19], s[4:5]
	s_cbranch_execz .LBB0_940
	s_waitcnt lgkmcnt(0)
	v_add_f32_e32 v22, v20, v21
	v_lshl_add_u64 v[20:21], v[126:127], 2, s[16:17]
	global_atomic_add_f32 v[20:21], v22, off
.LBB0_940:
	s_or_b64 exec, exec, s[18:19]
	s_waitcnt lgkmcnt(0)
	v_lshl_add_u64 v[20:21], s[14:15], 0, v[128:129]
	v_lshl_add_u64 v[24:25], v[202:203], 2, v[20:21]
	s_waitcnt vmcnt(20)
	v_pk_add_f32 v[18:19], v[18:19], v[90:91]
	v_pk_add_f32 v[16:17], v[16:17], v[88:89]
	v_pk_add_f32 v[14:15], v[14:15], v[82:83]
	v_pk_add_f32 v[12:13], v[12:13], v[80:81]
	global_store_dwordx4 v[24:25], v[16:19], off
	global_store_dwordx4 v[24:25], v[12:15], off offset:16
	v_cvt_pk_bf16_f32 v20, v16, v17
	s_waitcnt vmcnt(20)
	v_pk_add_f32 v[8:9], v[8:9], v[72:73]
	v_mul_f32_e32 v17, v17, v17
	v_fmac_f32_e32 v17, v16, v16
	v_fmac_f32_e32 v17, v18, v18
	v_fmac_f32_e32 v17, v19, v19
	v_fmac_f32_e32 v17, v12, v12
	v_cvt_pk_bf16_f32 v22, v12, v13
	v_fmac_f32_e32 v17, v13, v13
	v_pk_add_f32 v[12:13], v[4:5], v[68:69]
	v_mul_f32_e32 v4, v9, v9
	v_pk_add_f32 v[10:11], v[10:11], v[74:75]
	v_fmac_f32_e32 v4, v8, v8
	v_fmac_f32_e32 v4, v10, v10
	v_fmac_f32_e32 v4, v11, v11
	v_fmac_f32_e32 v17, v14, v14
	v_fmac_f32_e32 v4, v12, v12
	v_cvt_pk_bf16_f32 v23, v14, v15
	v_fmac_f32_e32 v17, v15, v15
	v_pk_add_f32 v[14:15], v[6:7], v[70:71]
	v_fmac_f32_e32 v4, v13, v13
	v_fmac_f32_e32 v4, v14, v14
	v_fmac_f32_e32 v4, v15, v15
	v_add_f32_e32 v4, v17, v4
	v_mov_b32_e32 v5, v4
	s_nop 1
	v_permlane16_swap_b32_e32 v4, v5
	v_lshlrev_b64 v[26:27], 12, v[124:125]
	v_lshl_add_u64 v[26:27], s[12:13], 0, v[26:27]
	v_cvt_pk_bf16_f32 v21, v18, v19
	v_lshl_add_u64 v[26:27], v[202:203], 1, v[26:27]
	s_waitcnt lgkmcnt(0)
	v_add_f32_e32 v4, v4, v5
	v_mov_b32_e32 v5, v4
	s_nop 1
	v_permlane32_swap_b32_e32 v4, v5
	global_store_dwordx4 v[26:27], v[20:23], off
	global_store_dwordx4 v[24:25], v[8:11], off offset:512
	global_store_dwordx4 v[24:25], v[12:15], off offset:528
	v_cvt_pk_bf16_f32 v6, v8, v9
	v_cvt_pk_bf16_f32 v7, v10, v11
	s_nop 0
	v_cvt_pk_bf16_f32 v8, v12, v13
	v_cvt_pk_bf16_f32 v9, v14, v15
	global_store_dwordx4 v[26:27], v[6:9], off offset:256
	s_and_saveexec_b64 s[18:19], s[4:5]
	s_cbranch_execz .LBB0_917
	s_waitcnt lgkmcnt(0)
	v_add_f32_e32 v6, v4, v5
	v_lshl_add_u64 v[4:5], v[124:125], 2, s[16:17]
	global_atomic_add_f32 v[4:5], v6, off
	s_branch .LBB0_917
